# hand-written radix-select top-k loop (pipelined ballots, SGPR threshold)
# speedup vs baseline: 1.0221x; 1.0221x over previous
; __device__ __forceinline__ void indexer_unit(const Args& a, LAS unsigned char* lds, LAS unsigned long long* maskl, int b, int qblk, int wave, int lane) {
;     ...
;     for (int qq = 0; qq < 2; ++qq) {
;         const int q = 2 * wave + qq, t = t0 + q, n = t + 1;
;         unsigned long long myword = 0ull;
;         if (n <= 256) {
;             const int lo = 64 * lane;
;             myword = (n >= lo + 64) ? ~0ull : (n > lo ? ((1ull << (n - lo)) - 1ull) : 0ull);
;         } else {
;             const int nr = __builtin_amdgcn_readfirstlane((n + 63) >> 6);
;             unsigned u[32];
; #pragma unroll
;             for (int r = 0; r < 32; ++r) u[r] = 0u;
; #pragma unroll
;             for (int g = 0; g < 8; ++g) if (4 * g < nr) {
; #pragma unroll
;                 for (int k4 = 0; k4 < 4; ++k4) { const int r = 4 * g + k4; const int idx = 64 * r + lane; const unsigned bits = __builtin_bit_cast(unsigned, sc[q * 2048 + idx]);
;                     const unsigned k = bits ^ (((unsigned)((int)bits >> 31)) | 0x80000000u); u[r] = idx < n ? k : 0u; } }
.LBB0_1101:
	s_xor_b64 s[0:1], s[0:1], -1
	v_writelane_b32 v254, s0, 48
	v_writelane_b32 v254, s1, 49
	s_lshl_b32 s0, s8, 12
	s_add_i32 s0, s0, 0x21000
	v_lshl_add_u32 v66, v5, 3, s0
	v_lshl_add_u32 v97, v5, 2, 0
	v_or_b32_e32 v67, 63, v84
	v_mov_b32_e32 v96, v5
	v_cmp_gt_u32_e64 s[6:7], 32, v5
	s_mov_b32 s9, 0
	s_barrier
.Ltk_q:
	s_or_b32 s77, s9, s85
	s_add_i32 s88, s77, s76
	s_cmpk_gt_u32 s88, 0xff
	s_cbranch_scc1 .Ltk_full
	v_sub_co_u32_e32 v0, vcc, s88, v84
	v_add_u32_e32 v0, 1, v0
	v_lshlrev_b64 v[0:1], v0, -1
	v_not_b32_e32 v1, v1
	v_not_b32_e32 v0, v0
	v_cndmask_b32_e64 v0, v0, 0, vcc
	v_cndmask_b32_e64 v1, v1, 0, vcc
	v_cmp_lt_u32_e32 vcc, s88, v67
	s_nop 1
	v_cndmask_b32_e32 v1, -1, v1, vcc
	v_cndmask_b32_e32 v0, -1, v0, vcc
	s_branch .Ltk_store
.Ltk_full:
	s_add_i32 s20, s88, 64
	s_lshr_b32 s20, s20, 6
	s_add_i32 s21, s20, 7
	s_lshr_b32 s21, s21, 3
	s_lshl_b32 s0, s77, 13
	v_add_u32_e32 v98, s0, v97
	ds_read2st64_b32 v[8:9], v98 offset0:0 offset1:1
	ds_read2st64_b32 v[10:11], v98 offset0:2 offset1:3
	ds_read2st64_b32 v[12:13], v98 offset0:4 offset1:5
	ds_read2st64_b32 v[14:15], v98 offset0:6 offset1:7
	s_mov_b32 s50, s88
	s_sub_i32 s51, s88, 64
	s_sub_i32 s52, s88, 128
	s_sub_i32 s53, s88, 192
	s_sub_i32 s54, s88, 256
	s_sub_i32 s55, s88, 320
	s_sub_i32 s56, s88, 384
	s_sub_i32 s57, s88, 448
	s_waitcnt lgkmcnt(0)
	v_ashrrev_i32_e32 v16, 31, v8
	v_ashrrev_i32_e32 v17, 31, v9
	v_ashrrev_i32_e32 v18, 31, v10
	v_ashrrev_i32_e32 v19, 31, v11
	v_ashrrev_i32_e32 v20, 31, v12
	v_ashrrev_i32_e32 v21, 31, v13
	v_ashrrev_i32_e32 v22, 31, v14
	v_ashrrev_i32_e32 v23, 31, v15
	v_bitop3_b32 v8, v16, v8, s89 bitop3:0x36
	v_bitop3_b32 v9, v17, v9, s89 bitop3:0x36
	v_bitop3_b32 v10, v18, v10, s89 bitop3:0x36
	v_bitop3_b32 v11, v19, v11, s89 bitop3:0x36
	v_bitop3_b32 v12, v20, v12, s89 bitop3:0x36
	v_bitop3_b32 v13, v21, v13, s89 bitop3:0x36
	v_bitop3_b32 v14, v22, v14, s89 bitop3:0x36
	v_bitop3_b32 v15, v23, v15, s89 bitop3:0x36
	v_cmp_ge_i32_e64 s[24:25], s50, v96
	v_cmp_ge_i32_e64 s[26:27], s51, v96
	v_cmp_ge_i32_e64 s[28:29], s52, v96
	v_cmp_ge_i32_e64 s[30:31], s53, v96
	v_cmp_ge_i32_e64 s[34:35], s54, v96
	v_cmp_ge_i32_e64 s[36:37], s55, v96
	v_cmp_ge_i32_e64 s[38:39], s56, v96
	v_cmp_ge_i32_e64 s[40:41], s57, v96
	v_cndmask_b32_e64 v32, 0, v8, s[24:25]
	v_cndmask_b32_e64 v33, 0, v9, s[26:27]
	v_cndmask_b32_e64 v34, 0, v10, s[28:29]
	v_cndmask_b32_e64 v35, 0, v11, s[30:31]
	v_cndmask_b32_e64 v36, 0, v12, s[34:35]
	v_cndmask_b32_e64 v37, 0, v13, s[36:37]
	v_cndmask_b32_e64 v38, 0, v14, s[38:39]
	v_cndmask_b32_e64 v39, 0, v15, s[40:41]
	s_cmp_lt_u32 s21, 2
	s_cbranch_scc1 .Ltk_ld_done
	ds_read2st64_b32 v[8:9], v98 offset0:8 offset1:9
	ds_read2st64_b32 v[10:11], v98 offset0:10 offset1:11
	ds_read2st64_b32 v[12:13], v98 offset0:12 offset1:13
	ds_read2st64_b32 v[14:15], v98 offset0:14 offset1:15
	s_sub_i32 s50, s88, 512
	s_sub_i32 s51, s88, 576
	s_sub_i32 s52, s88, 640
	s_sub_i32 s53, s88, 704
	s_sub_i32 s54, s88, 768
	s_sub_i32 s55, s88, 832
	s_sub_i32 s56, s88, 896
	s_sub_i32 s57, s88, 960
	s_waitcnt lgkmcnt(0)
	v_ashrrev_i32_e32 v16, 31, v8
	v_ashrrev_i32_e32 v17, 31, v9
	v_ashrrev_i32_e32 v18, 31, v10
	v_ashrrev_i32_e32 v19, 31, v11
	v_ashrrev_i32_e32 v20, 31, v12
	v_ashrrev_i32_e32 v21, 31, v13
	v_ashrrev_i32_e32 v22, 31, v14
	v_ashrrev_i32_e32 v23, 31, v15
	v_bitop3_b32 v8, v16, v8, s89 bitop3:0x36
	v_bitop3_b32 v9, v17, v9, s89 bitop3:0x36
	v_bitop3_b32 v10, v18, v10, s89 bitop3:0x36
	v_bitop3_b32 v11, v19, v11, s89 bitop3:0x36
	v_bitop3_b32 v12, v20, v12, s89 bitop3:0x36
	v_bitop3_b32 v13, v21, v13, s89 bitop3:0x36
	v_bitop3_b32 v14, v22, v14, s89 bitop3:0x36
	v_bitop3_b32 v15, v23, v15, s89 bitop3:0x36
	v_cmp_ge_i32_e64 s[24:25], s50, v96
	v_cmp_ge_i32_e64 s[26:27], s51, v96
	v_cmp_ge_i32_e64 s[28:29], s52, v96
	v_cmp_ge_i32_e64 s[30:31], s53, v96
	v_cmp_ge_i32_e64 s[34:35], s54, v96
	v_cmp_ge_i32_e64 s[36:37], s55, v96
	v_cmp_ge_i32_e64 s[38:39], s56, v96
	v_cmp_ge_i32_e64 s[40:41], s57, v96
	v_cndmask_b32_e64 v40, 0, v8, s[24:25]
	v_cndmask_b32_e64 v41, 0, v9, s[26:27]
	v_cndmask_b32_e64 v42, 0, v10, s[28:29]
	v_cndmask_b32_e64 v43, 0, v11, s[30:31]
	v_cndmask_b32_e64 v44, 0, v12, s[34:35]
	v_cndmask_b32_e64 v45, 0, v13, s[36:37]
	v_cndmask_b32_e64 v46, 0, v14, s[38:39]
	v_cndmask_b32_e64 v47, 0, v15, s[40:41]
	s_cmp_lt_u32 s21, 3
	s_cbranch_scc1 .Ltk_ld_done
	ds_read2st64_b32 v[8:9], v98 offset0:16 offset1:17
	ds_read2st64_b32 v[10:11], v98 offset0:18 offset1:19
	ds_read2st64_b32 v[12:13], v98 offset0:20 offset1:21
	ds_read2st64_b32 v[14:15], v98 offset0:22 offset1:23
	s_sub_i32 s50, s88, 1024
	s_sub_i32 s51, s88, 1088
	s_sub_i32 s52, s88, 1152
	s_sub_i32 s53, s88, 1216
	s_sub_i32 s54, s88, 1280
	s_sub_i32 s55, s88, 1344
	s_sub_i32 s56, s88, 1408
	s_sub_i32 s57, s88, 1472
	s_waitcnt lgkmcnt(0)
	v_ashrrev_i32_e32 v16, 31, v8
	v_ashrrev_i32_e32 v17, 31, v9
	v_ashrrev_i32_e32 v18, 31, v10
	v_ashrrev_i32_e32 v19, 31, v11
	v_ashrrev_i32_e32 v20, 31, v12
	v_ashrrev_i32_e32 v21, 31, v13
	v_ashrrev_i32_e32 v22, 31, v14
	v_ashrrev_i32_e32 v23, 31, v15
	v_bitop3_b32 v8, v16, v8, s89 bitop3:0x36
	v_bitop3_b32 v9, v17, v9, s89 bitop3:0x36
	v_bitop3_b32 v10, v18, v10, s89 bitop3:0x36
	v_bitop3_b32 v11, v19, v11, s89 bitop3:0x36
	v_bitop3_b32 v12, v20, v12, s89 bitop3:0x36
	v_bitop3_b32 v13, v21, v13, s89 bitop3:0x36
	v_bitop3_b32 v14, v22, v14, s89 bitop3:0x36
	v_bitop3_b32 v15, v23, v15, s89 bitop3:0x36
	v_cmp_ge_i32_e64 s[24:25], s50, v96
	v_cmp_ge_i32_e64 s[26:27], s51, v96
	v_cmp_ge_i32_e64 s[28:29], s52, v96
	v_cmp_ge_i32_e64 s[30:31], s53, v96
	v_cmp_ge_i32_e64 s[34:35], s54, v96
	v_cmp_ge_i32_e64 s[36:37], s55, v96
	v_cmp_ge_i32_e64 s[38:39], s56, v96
	v_cmp_ge_i32_e64 s[40:41], s57, v96
	v_cndmask_b32_e64 v48, 0, v8, s[24:25]
	v_cndmask_b32_e64 v49, 0, v9, s[26:27]
	v_cndmask_b32_e64 v50, 0, v10, s[28:29]
	v_cndmask_b32_e64 v51, 0, v11, s[30:31]
	v_cndmask_b32_e64 v52, 0, v12, s[34:35]
	v_cndmask_b32_e64 v53, 0, v13, s[36:37]
	v_cndmask_b32_e64 v54, 0, v14, s[38:39]
	v_cndmask_b32_e64 v55, 0, v15, s[40:41]
	s_cmp_lt_u32 s21, 4
	s_cbranch_scc1 .Ltk_ld_done
; #define TK_GRP(g) { const int c0 = __popcll(__ballot(u[4 * (g)] >= cand)), c1 = __popcll(__ballot(u[4 * (g) + 1] >= cand)), c2 = __popcll(__ballot(u[4 * (g) + 2] >= cand)), c3 = __popcll(__ballot(u[4 * (g) + 3] >= cand)); cnt += (c0 + c1) + (c2 + c3); }
; __device__ __forceinline__ void indexer_unit(const Args& a, LAS unsigned char* lds, LAS unsigned long long* maskl, int b, int qblk, int wave, int lane) {
;     ...
;             for (int g = 0; g < 8; ++g) if (4 * g < nr) {
; #pragma unroll
;                 for (int k4 = 0; k4 < 4; ++k4) { const int r = 4 * g + k4; const int idx = 64 * r + lane; const unsigned bits = __builtin_bit_cast(unsigned, sc[q * 2048 + idx]);
;                     const unsigned k = bits ^ (((unsigned)((int)bits >> 31)) | 0x80000000u); u[r] = idx < n ? k : 0u; } }
;             unsigned T = 0u; bool exact = false; const int ng = (nr + 3) >> 2;
; #pragma unroll 1
;     ...
;                 const unsigned cand = T | (1u << bit); int cnt = 0;
;     ...
;                 switch (ng) {
;                     case 8: TK_GRP(7) [[fallthrough]];
;                     case 7: TK_GRP(6) [[fallthrough]];
;                     case 6: TK_GRP(5) [[fallthrough]];
;                     case 5: TK_GRP(4) [[fallthrough]];
;                     case 4: TK_GRP(3) [[fallthrough]];
;                     case 3: TK_GRP(2) [[fallthrough]];
;                     case 2: TK_GRP(1) [[fallthrough]];
;                     default: TK_GRP(0)
;                 }
;     ...
;                 if (cnt >= 256) { T = cand; if (cnt == 256) { exact = true; break; } }
;             }
	ds_read2st64_b32 v[8:9], v98 offset0:24 offset1:25
	ds_read2st64_b32 v[10:11], v98 offset0:26 offset1:27
	ds_read2st64_b32 v[12:13], v98 offset0:28 offset1:29
	ds_read2st64_b32 v[14:15], v98 offset0:30 offset1:31
	s_sub_i32 s50, s88, 1536
	s_sub_i32 s51, s88, 1600
	s_sub_i32 s52, s88, 1664
	s_sub_i32 s53, s88, 1728
	s_sub_i32 s54, s88, 1792
	s_sub_i32 s55, s88, 1856
	s_sub_i32 s56, s88, 1920
	s_sub_i32 s57, s88, 1984
	s_waitcnt lgkmcnt(0)
	v_ashrrev_i32_e32 v16, 31, v8
	v_ashrrev_i32_e32 v17, 31, v9
	v_ashrrev_i32_e32 v18, 31, v10
	v_ashrrev_i32_e32 v19, 31, v11
	v_ashrrev_i32_e32 v20, 31, v12
	v_ashrrev_i32_e32 v21, 31, v13
	v_ashrrev_i32_e32 v22, 31, v14
	v_ashrrev_i32_e32 v23, 31, v15
	v_bitop3_b32 v8, v16, v8, s89 bitop3:0x36
	v_bitop3_b32 v9, v17, v9, s89 bitop3:0x36
	v_bitop3_b32 v10, v18, v10, s89 bitop3:0x36
	v_bitop3_b32 v11, v19, v11, s89 bitop3:0x36
	v_bitop3_b32 v12, v20, v12, s89 bitop3:0x36
	v_bitop3_b32 v13, v21, v13, s89 bitop3:0x36
	v_bitop3_b32 v14, v22, v14, s89 bitop3:0x36
	v_bitop3_b32 v15, v23, v15, s89 bitop3:0x36
	v_cmp_ge_i32_e64 s[24:25], s50, v96
	v_cmp_ge_i32_e64 s[26:27], s51, v96
	v_cmp_ge_i32_e64 s[28:29], s52, v96
	v_cmp_ge_i32_e64 s[30:31], s53, v96
	v_cmp_ge_i32_e64 s[34:35], s54, v96
	v_cmp_ge_i32_e64 s[36:37], s55, v96
	v_cmp_ge_i32_e64 s[38:39], s56, v96
	v_cmp_ge_i32_e64 s[40:41], s57, v96
	v_cndmask_b32_e64 v56, 0, v8, s[24:25]
	v_cndmask_b32_e64 v57, 0, v9, s[26:27]
	v_cndmask_b32_e64 v58, 0, v10, s[28:29]
	v_cndmask_b32_e64 v59, 0, v11, s[30:31]
	v_cndmask_b32_e64 v60, 0, v12, s[34:35]
	v_cndmask_b32_e64 v61, 0, v13, s[36:37]
	v_cndmask_b32_e64 v62, 0, v14, s[38:39]
	v_cndmask_b32_e64 v63, 0, v15, s[40:41]
.Ltk_ld_done:
	s_mov_b32 s10, 0
	s_mov_b32 s11, 31
.Ltk_bit:
	s_lshl_b32 s12, 1, s11
	s_or_b32 s13, s10, s12
	v_cmp_le_u32_e64 s[24:25], s13, v32
	v_cmp_le_u32_e64 s[26:27], s13, v33
	v_cmp_le_u32_e64 s[28:29], s13, v34
	v_cmp_le_u32_e64 s[30:31], s13, v35
	v_cmp_le_u32_e64 s[34:35], s13, v36
	v_cmp_le_u32_e64 s[36:37], s13, v37
	v_cmp_le_u32_e64 s[38:39], s13, v38
	v_cmp_le_u32_e64 s[40:41], s13, v39
	s_bcnt1_i32_b64 s42, s[24:25]
	s_bcnt1_i32_b64 s43, s[26:27]
	s_bcnt1_i32_b64 s44, s[28:29]
	s_bcnt1_i32_b64 s45, s[30:31]
	s_bcnt1_i32_b64 s46, s[34:35]
	s_bcnt1_i32_b64 s47, s[36:37]
	s_bcnt1_i32_b64 s48, s[38:39]
	s_bcnt1_i32_b64 s49, s[40:41]
	s_add_i32 s14, s42, s43
	s_add_i32 s14, s14, s44
	s_add_i32 s14, s14, s45
	s_add_i32 s14, s14, s46
	s_add_i32 s14, s14, s47
	s_add_i32 s14, s14, s48
	s_add_i32 s14, s14, s49
	s_cmp_lt_u32 s21, 2
	s_cbranch_scc1 .Ltk_dec
	v_cmp_le_u32_e64 s[24:25], s13, v40
	v_cmp_le_u32_e64 s[26:27], s13, v41
	v_cmp_le_u32_e64 s[28:29], s13, v42
	v_cmp_le_u32_e64 s[30:31], s13, v43
	v_cmp_le_u32_e64 s[34:35], s13, v44
	v_cmp_le_u32_e64 s[36:37], s13, v45
	v_cmp_le_u32_e64 s[38:39], s13, v46
	v_cmp_le_u32_e64 s[40:41], s13, v47
	s_bcnt1_i32_b64 s42, s[24:25]
	s_bcnt1_i32_b64 s43, s[26:27]
	s_bcnt1_i32_b64 s44, s[28:29]
	s_bcnt1_i32_b64 s45, s[30:31]
	s_bcnt1_i32_b64 s46, s[34:35]
	s_bcnt1_i32_b64 s47, s[36:37]
	s_bcnt1_i32_b64 s48, s[38:39]
	s_bcnt1_i32_b64 s49, s[40:41]
	s_add_i32 s14, s14, s42
	s_add_i32 s14, s14, s43
	s_add_i32 s14, s14, s44
	s_add_i32 s14, s14, s45
	s_add_i32 s14, s14, s46
	s_add_i32 s14, s14, s47
	s_add_i32 s14, s14, s48
	s_add_i32 s14, s14, s49
	s_cmp_lt_u32 s21, 3
	s_cbranch_scc1 .Ltk_dec
	v_cmp_le_u32_e64 s[24:25], s13, v48
	v_cmp_le_u32_e64 s[26:27], s13, v49
	v_cmp_le_u32_e64 s[28:29], s13, v50
	v_cmp_le_u32_e64 s[30:31], s13, v51
	v_cmp_le_u32_e64 s[34:35], s13, v52
	v_cmp_le_u32_e64 s[36:37], s13, v53
	v_cmp_le_u32_e64 s[38:39], s13, v54
	v_cmp_le_u32_e64 s[40:41], s13, v55
	s_bcnt1_i32_b64 s42, s[24:25]
	s_bcnt1_i32_b64 s43, s[26:27]
	s_bcnt1_i32_b64 s44, s[28:29]
	s_bcnt1_i32_b64 s45, s[30:31]
	s_bcnt1_i32_b64 s46, s[34:35]
	s_bcnt1_i32_b64 s47, s[36:37]
	s_bcnt1_i32_b64 s48, s[38:39]
	s_bcnt1_i32_b64 s49, s[40:41]
	s_add_i32 s14, s14, s42
	s_add_i32 s14, s14, s43
	s_add_i32 s14, s14, s44
	s_add_i32 s14, s14, s45
	s_add_i32 s14, s14, s46
	s_add_i32 s14, s14, s47
	s_add_i32 s14, s14, s48
	s_add_i32 s14, s14, s49
	s_cmp_lt_u32 s21, 4
	s_cbranch_scc1 .Ltk_dec
	v_cmp_le_u32_e64 s[24:25], s13, v56
	v_cmp_le_u32_e64 s[26:27], s13, v57
	v_cmp_le_u32_e64 s[28:29], s13, v58
	v_cmp_le_u32_e64 s[30:31], s13, v59
	v_cmp_le_u32_e64 s[34:35], s13, v60
	v_cmp_le_u32_e64 s[36:37], s13, v61
	v_cmp_le_u32_e64 s[38:39], s13, v62
	v_cmp_le_u32_e64 s[40:41], s13, v63
	s_bcnt1_i32_b64 s42, s[24:25]
	s_bcnt1_i32_b64 s43, s[26:27]
	s_bcnt1_i32_b64 s44, s[28:29]
	s_bcnt1_i32_b64 s45, s[30:31]
	s_bcnt1_i32_b64 s46, s[34:35]
	s_bcnt1_i32_b64 s47, s[36:37]
	s_bcnt1_i32_b64 s48, s[38:39]
	s_bcnt1_i32_b64 s49, s[40:41]
	s_add_i32 s14, s14, s42
	s_add_i32 s14, s14, s43
	s_add_i32 s14, s14, s44
	s_add_i32 s14, s14, s45
	s_add_i32 s14, s14, s46
	s_add_i32 s14, s14, s47
	s_add_i32 s14, s14, s48
	s_add_i32 s14, s14, s49
.Ltk_dec:
	s_cmpk_lt_u32 s14, 0x100
	s_cbranch_scc1 .Ltk_nxt
	s_mov_b32 s10, s13
	s_cmpk_eq_u32 s14, 0x100
	s_cbranch_scc1 .Ltk_exact
; __device__ __forceinline__ void indexer_unit(const Args& a, LAS unsigned char* lds, LAS unsigned long long* maskl, int b, int qblk, int wave, int lane) {
;     ...
;                 if (cnt >= 256) { T = cand; if (cnt == 256) { exact = true; break; } }
;             }
;             int need = 0; const unsigned long long lt = (1ull << lane) - 1ull;
;             if (!exact) {
;                 int cl = 0;
; #pragma unroll
;                 for (int r = 0; r < 32; ++r) cl += (u[r] > T) ? 1 : 0;
;                 int ngt = 0;
; #pragma unroll
;                 for (int bb = 0; bb < 6; ++bb) ngt += __popcll(__ballot((cl >> bb) & 1)) << bb;
;                 need = 256 - ngt;
;             }
; #pragma unroll
;             for (int g = 0; g < 8; ++g) if (4 * g < nr) {
; #pragma unroll
;                 for (int k = 0; k < 4; ++k) { const int r = 4 * g + k;
;                     unsigned ur = u[r]; asm volatile("" : "+v"(ur), "+v"(myword), "+s"(need));
;                     unsigned long long m;
;                     if (exact) m = __ballot(ur >= T);
;                     else { const unsigned long long eq = __ballot(ur == T), gt = __ballot(ur > T);
;                         const bool pick = (ur == T) && (__popcll(eq & lt) < need);
;                         m = gt | __ballot(pick); need -= __popcll(eq); if (need < 0) need = 0; }
;                     if (lane == r) myword = m; } }
.Ltk_nxt:
	s_add_i32 s11, s11, -1
	s_cmp_ge_i32 s11, 0
	s_cbranch_scc1 .Ltk_bit
	v_mov_b32_e32 v0, 0
	v_mov_b32_e32 v1, 0
	v_cmp_lt_u32_e64 s[24:25], s10, v32
	v_cmp_lt_u32_e64 s[26:27], s10, v33
	v_cmp_lt_u32_e64 s[28:29], s10, v34
	v_cmp_lt_u32_e64 s[30:31], s10, v35
	v_cmp_lt_u32_e64 s[34:35], s10, v36
	v_cmp_lt_u32_e64 s[36:37], s10, v37
	v_cmp_lt_u32_e64 s[38:39], s10, v38
	v_cmp_lt_u32_e64 s[40:41], s10, v39
	s_bcnt1_i32_b64 s42, s[24:25]
	s_bcnt1_i32_b64 s43, s[26:27]
	s_bcnt1_i32_b64 s44, s[28:29]
	s_bcnt1_i32_b64 s45, s[30:31]
	s_bcnt1_i32_b64 s46, s[34:35]
	s_bcnt1_i32_b64 s47, s[36:37]
	s_bcnt1_i32_b64 s48, s[38:39]
	s_bcnt1_i32_b64 s49, s[40:41]
	s_add_i32 s14, s42, s43
	s_add_i32 s14, s14, s44
	s_add_i32 s14, s14, s45
	s_add_i32 s14, s14, s46
	s_add_i32 s14, s14, s47
	s_add_i32 s14, s14, s48
	s_add_i32 s14, s14, s49
	s_cmp_lt_u32 s21, 2
	s_cbranch_scc1 .Ltk_tie_cnt_done
	v_cmp_lt_u32_e64 s[24:25], s10, v40
	v_cmp_lt_u32_e64 s[26:27], s10, v41
	v_cmp_lt_u32_e64 s[28:29], s10, v42
	v_cmp_lt_u32_e64 s[30:31], s10, v43
	v_cmp_lt_u32_e64 s[34:35], s10, v44
	v_cmp_lt_u32_e64 s[36:37], s10, v45
	v_cmp_lt_u32_e64 s[38:39], s10, v46
	v_cmp_lt_u32_e64 s[40:41], s10, v47
	s_bcnt1_i32_b64 s42, s[24:25]
	s_bcnt1_i32_b64 s43, s[26:27]
	s_bcnt1_i32_b64 s44, s[28:29]
	s_bcnt1_i32_b64 s45, s[30:31]
	s_bcnt1_i32_b64 s46, s[34:35]
	s_bcnt1_i32_b64 s47, s[36:37]
	s_bcnt1_i32_b64 s48, s[38:39]
	s_bcnt1_i32_b64 s49, s[40:41]
	s_add_i32 s14, s14, s42
	s_add_i32 s14, s14, s43
	s_add_i32 s14, s14, s44
	s_add_i32 s14, s14, s45
	s_add_i32 s14, s14, s46
	s_add_i32 s14, s14, s47
	s_add_i32 s14, s14, s48
	s_add_i32 s14, s14, s49
	s_cmp_lt_u32 s21, 3
	s_cbranch_scc1 .Ltk_tie_cnt_done
	v_cmp_lt_u32_e64 s[24:25], s10, v48
	v_cmp_lt_u32_e64 s[26:27], s10, v49
	v_cmp_lt_u32_e64 s[28:29], s10, v50
	v_cmp_lt_u32_e64 s[30:31], s10, v51
	v_cmp_lt_u32_e64 s[34:35], s10, v52
	v_cmp_lt_u32_e64 s[36:37], s10, v53
	v_cmp_lt_u32_e64 s[38:39], s10, v54
	v_cmp_lt_u32_e64 s[40:41], s10, v55
	s_bcnt1_i32_b64 s42, s[24:25]
	s_bcnt1_i32_b64 s43, s[26:27]
	s_bcnt1_i32_b64 s44, s[28:29]
	s_bcnt1_i32_b64 s45, s[30:31]
	s_bcnt1_i32_b64 s46, s[34:35]
	s_bcnt1_i32_b64 s47, s[36:37]
	s_bcnt1_i32_b64 s48, s[38:39]
	s_bcnt1_i32_b64 s49, s[40:41]
	s_add_i32 s14, s14, s42
	s_add_i32 s14, s14, s43
	s_add_i32 s14, s14, s44
	s_add_i32 s14, s14, s45
	s_add_i32 s14, s14, s46
	s_add_i32 s14, s14, s47
	s_add_i32 s14, s14, s48
	s_add_i32 s14, s14, s49
	s_cmp_lt_u32 s21, 4
	s_cbranch_scc1 .Ltk_tie_cnt_done
	v_cmp_lt_u32_e64 s[24:25], s10, v56
	v_cmp_lt_u32_e64 s[26:27], s10, v57
	v_cmp_lt_u32_e64 s[28:29], s10, v58
	v_cmp_lt_u32_e64 s[30:31], s10, v59
	v_cmp_lt_u32_e64 s[34:35], s10, v60
	v_cmp_lt_u32_e64 s[36:37], s10, v61
	v_cmp_lt_u32_e64 s[38:39], s10, v62
	v_cmp_lt_u32_e64 s[40:41], s10, v63
	s_bcnt1_i32_b64 s42, s[24:25]
	s_bcnt1_i32_b64 s43, s[26:27]
	s_bcnt1_i32_b64 s44, s[28:29]
	s_bcnt1_i32_b64 s45, s[30:31]
	s_bcnt1_i32_b64 s46, s[34:35]
	s_bcnt1_i32_b64 s47, s[36:37]
	s_bcnt1_i32_b64 s48, s[38:39]
	s_bcnt1_i32_b64 s49, s[40:41]
	s_add_i32 s14, s14, s42
	s_add_i32 s14, s14, s43
	s_add_i32 s14, s14, s44
	s_add_i32 s14, s14, s45
	s_add_i32 s14, s14, s46
	s_add_i32 s14, s14, s47
	s_add_i32 s14, s14, s48
	s_add_i32 s14, s14, s49
.Ltk_tie_cnt_done:
	s_sub_i32 s16, 0x100, s14
	v_cmp_eq_u32_e64 s[24:25], s10, v32
	v_cmp_lt_u32_e64 s[26:27], s10, v32
	s_bcnt1_i32_b64 s17, s[24:25]
	s_nop 0
	v_mbcnt_lo_u32_b32 v2, s24, 0
	v_mbcnt_hi_u32_b32 v2, s25, v2
	v_cmp_gt_u32_e64 s[28:29], s16, v2
	s_and_b64 s[28:29], s[28:29], s[24:25]
	s_or_b64 s[26:27], s[26:27], s[28:29]
	s_sub_i32 s16, s16, s17
	s_max_i32 s16, s16, 0
	v_writelane_b32 v0, s26, 0
	v_writelane_b32 v1, s27, 0
	v_cmp_eq_u32_e64 s[24:25], s10, v33
	v_cmp_lt_u32_e64 s[26:27], s10, v33
	s_bcnt1_i32_b64 s17, s[24:25]
	s_nop 0
	v_mbcnt_lo_u32_b32 v2, s24, 0
	v_mbcnt_hi_u32_b32 v2, s25, v2
	v_cmp_gt_u32_e64 s[28:29], s16, v2
	s_and_b64 s[28:29], s[28:29], s[24:25]
	s_or_b64 s[26:27], s[26:27], s[28:29]
	s_sub_i32 s16, s16, s17
	s_max_i32 s16, s16, 0
	v_writelane_b32 v0, s26, 1
	v_writelane_b32 v1, s27, 1
	v_cmp_eq_u32_e64 s[24:25], s10, v34
	v_cmp_lt_u32_e64 s[26:27], s10, v34
	s_bcnt1_i32_b64 s17, s[24:25]
	s_nop 0
	v_mbcnt_lo_u32_b32 v2, s24, 0
	v_mbcnt_hi_u32_b32 v2, s25, v2
	v_cmp_gt_u32_e64 s[28:29], s16, v2
	s_and_b64 s[28:29], s[28:29], s[24:25]
	s_or_b64 s[26:27], s[26:27], s[28:29]
	s_sub_i32 s16, s16, s17
	s_max_i32 s16, s16, 0
	v_writelane_b32 v0, s26, 2
	v_writelane_b32 v1, s27, 2
	v_cmp_eq_u32_e64 s[24:25], s10, v35
	v_cmp_lt_u32_e64 s[26:27], s10, v35
	s_bcnt1_i32_b64 s17, s[24:25]
	s_nop 0
	v_mbcnt_lo_u32_b32 v2, s24, 0
	v_mbcnt_hi_u32_b32 v2, s25, v2
	v_cmp_gt_u32_e64 s[28:29], s16, v2
	s_and_b64 s[28:29], s[28:29], s[24:25]
	s_or_b64 s[26:27], s[26:27], s[28:29]
	s_sub_i32 s16, s16, s17
	s_max_i32 s16, s16, 0
	v_writelane_b32 v0, s26, 3
	v_writelane_b32 v1, s27, 3
	v_cmp_eq_u32_e64 s[24:25], s10, v36
	v_cmp_lt_u32_e64 s[26:27], s10, v36
	s_bcnt1_i32_b64 s17, s[24:25]
	s_nop 0
	v_mbcnt_lo_u32_b32 v2, s24, 0
	v_mbcnt_hi_u32_b32 v2, s25, v2
	v_cmp_gt_u32_e64 s[28:29], s16, v2
	s_and_b64 s[28:29], s[28:29], s[24:25]
	s_or_b64 s[26:27], s[26:27], s[28:29]
	s_sub_i32 s16, s16, s17
	s_max_i32 s16, s16, 0
	v_writelane_b32 v0, s26, 4
	v_writelane_b32 v1, s27, 4
	v_cmp_eq_u32_e64 s[24:25], s10, v37
	v_cmp_lt_u32_e64 s[26:27], s10, v37
	s_bcnt1_i32_b64 s17, s[24:25]
	s_nop 0
	v_mbcnt_lo_u32_b32 v2, s24, 0
	v_mbcnt_hi_u32_b32 v2, s25, v2
	v_cmp_gt_u32_e64 s[28:29], s16, v2
	s_and_b64 s[28:29], s[28:29], s[24:25]
	s_or_b64 s[26:27], s[26:27], s[28:29]
	s_sub_i32 s16, s16, s17
	s_max_i32 s16, s16, 0
	v_writelane_b32 v0, s26, 5
	v_writelane_b32 v1, s27, 5
	v_cmp_eq_u32_e64 s[24:25], s10, v38
	v_cmp_lt_u32_e64 s[26:27], s10, v38
	s_bcnt1_i32_b64 s17, s[24:25]
	s_nop 0
	v_mbcnt_lo_u32_b32 v2, s24, 0
	v_mbcnt_hi_u32_b32 v2, s25, v2
	v_cmp_gt_u32_e64 s[28:29], s16, v2
	s_and_b64 s[28:29], s[28:29], s[24:25]
	s_or_b64 s[26:27], s[26:27], s[28:29]
	s_sub_i32 s16, s16, s17
	s_max_i32 s16, s16, 0
	v_writelane_b32 v0, s26, 6
	v_writelane_b32 v1, s27, 6
	v_cmp_eq_u32_e64 s[24:25], s10, v39
	v_cmp_lt_u32_e64 s[26:27], s10, v39
	s_bcnt1_i32_b64 s17, s[24:25]
	s_nop 0
	v_mbcnt_lo_u32_b32 v2, s24, 0
	v_mbcnt_hi_u32_b32 v2, s25, v2
	v_cmp_gt_u32_e64 s[28:29], s16, v2
	s_and_b64 s[28:29], s[28:29], s[24:25]
	s_or_b64 s[26:27], s[26:27], s[28:29]
	s_sub_i32 s16, s16, s17
	s_max_i32 s16, s16, 0
	v_writelane_b32 v0, s26, 7
	v_writelane_b32 v1, s27, 7
	s_cmp_lt_u32 s21, 2
	s_cbranch_scc1 .Ltk_store
; __device__ __forceinline__ void indexer_unit(const Args& a, LAS unsigned char* lds, LAS unsigned long long* maskl, int b, int qblk, int wave, int lane) {
;     ...
; #pragma unroll
;             for (int g = 0; g < 8; ++g) if (4 * g < nr) {
; #pragma unroll
;                 for (int k = 0; k < 4; ++k) { const int r = 4 * g + k;
;                     unsigned ur = u[r]; asm volatile("" : "+v"(ur), "+v"(myword), "+s"(need));
;                     unsigned long long m;
;                     if (exact) m = __ballot(ur >= T);
;                     else { const unsigned long long eq = __ballot(ur == T), gt = __ballot(ur > T);
;                         const bool pick = (ur == T) && (__popcll(eq & lt) < need);
;                         m = gt | __ballot(pick); need -= __popcll(eq); if (need < 0) need = 0; }
;                     if (lane == r) myword = m; } }
	v_cmp_eq_u32_e64 s[24:25], s10, v40
	v_cmp_lt_u32_e64 s[26:27], s10, v40
	s_bcnt1_i32_b64 s17, s[24:25]
	s_nop 0
	v_mbcnt_lo_u32_b32 v2, s24, 0
	v_mbcnt_hi_u32_b32 v2, s25, v2
	v_cmp_gt_u32_e64 s[28:29], s16, v2
	s_and_b64 s[28:29], s[28:29], s[24:25]
	s_or_b64 s[26:27], s[26:27], s[28:29]
	s_sub_i32 s16, s16, s17
	s_max_i32 s16, s16, 0
	v_writelane_b32 v0, s26, 8
	v_writelane_b32 v1, s27, 8
	v_cmp_eq_u32_e64 s[24:25], s10, v41
	v_cmp_lt_u32_e64 s[26:27], s10, v41
	s_bcnt1_i32_b64 s17, s[24:25]
	s_nop 0
	v_mbcnt_lo_u32_b32 v2, s24, 0
	v_mbcnt_hi_u32_b32 v2, s25, v2
	v_cmp_gt_u32_e64 s[28:29], s16, v2
	s_and_b64 s[28:29], s[28:29], s[24:25]
	s_or_b64 s[26:27], s[26:27], s[28:29]
	s_sub_i32 s16, s16, s17
	s_max_i32 s16, s16, 0
	v_writelane_b32 v0, s26, 9
	v_writelane_b32 v1, s27, 9
	v_cmp_eq_u32_e64 s[24:25], s10, v42
	v_cmp_lt_u32_e64 s[26:27], s10, v42
	s_bcnt1_i32_b64 s17, s[24:25]
	s_nop 0
	v_mbcnt_lo_u32_b32 v2, s24, 0
	v_mbcnt_hi_u32_b32 v2, s25, v2
	v_cmp_gt_u32_e64 s[28:29], s16, v2
	s_and_b64 s[28:29], s[28:29], s[24:25]
	s_or_b64 s[26:27], s[26:27], s[28:29]
	s_sub_i32 s16, s16, s17
	s_max_i32 s16, s16, 0
	v_writelane_b32 v0, s26, 10
	v_writelane_b32 v1, s27, 10
	v_cmp_eq_u32_e64 s[24:25], s10, v43
	v_cmp_lt_u32_e64 s[26:27], s10, v43
	s_bcnt1_i32_b64 s17, s[24:25]
	s_nop 0
	v_mbcnt_lo_u32_b32 v2, s24, 0
	v_mbcnt_hi_u32_b32 v2, s25, v2
	v_cmp_gt_u32_e64 s[28:29], s16, v2
	s_and_b64 s[28:29], s[28:29], s[24:25]
	s_or_b64 s[26:27], s[26:27], s[28:29]
	s_sub_i32 s16, s16, s17
	s_max_i32 s16, s16, 0
	v_writelane_b32 v0, s26, 11
	v_writelane_b32 v1, s27, 11
	v_cmp_eq_u32_e64 s[24:25], s10, v44
	v_cmp_lt_u32_e64 s[26:27], s10, v44
	s_bcnt1_i32_b64 s17, s[24:25]
	s_nop 0
	v_mbcnt_lo_u32_b32 v2, s24, 0
	v_mbcnt_hi_u32_b32 v2, s25, v2
	v_cmp_gt_u32_e64 s[28:29], s16, v2
	s_and_b64 s[28:29], s[28:29], s[24:25]
	s_or_b64 s[26:27], s[26:27], s[28:29]
	s_sub_i32 s16, s16, s17
	s_max_i32 s16, s16, 0
	v_writelane_b32 v0, s26, 12
	v_writelane_b32 v1, s27, 12
	v_cmp_eq_u32_e64 s[24:25], s10, v45
	v_cmp_lt_u32_e64 s[26:27], s10, v45
	s_bcnt1_i32_b64 s17, s[24:25]
	s_nop 0
	v_mbcnt_lo_u32_b32 v2, s24, 0
	v_mbcnt_hi_u32_b32 v2, s25, v2
	v_cmp_gt_u32_e64 s[28:29], s16, v2
	s_and_b64 s[28:29], s[28:29], s[24:25]
	s_or_b64 s[26:27], s[26:27], s[28:29]
	s_sub_i32 s16, s16, s17
	s_max_i32 s16, s16, 0
	v_writelane_b32 v0, s26, 13
	v_writelane_b32 v1, s27, 13
	v_cmp_eq_u32_e64 s[24:25], s10, v46
	v_cmp_lt_u32_e64 s[26:27], s10, v46
	s_bcnt1_i32_b64 s17, s[24:25]
	s_nop 0
	v_mbcnt_lo_u32_b32 v2, s24, 0
	v_mbcnt_hi_u32_b32 v2, s25, v2
	v_cmp_gt_u32_e64 s[28:29], s16, v2
	s_and_b64 s[28:29], s[28:29], s[24:25]
	s_or_b64 s[26:27], s[26:27], s[28:29]
	s_sub_i32 s16, s16, s17
	s_max_i32 s16, s16, 0
	v_writelane_b32 v0, s26, 14
	v_writelane_b32 v1, s27, 14
	v_cmp_eq_u32_e64 s[24:25], s10, v47
	v_cmp_lt_u32_e64 s[26:27], s10, v47
	s_bcnt1_i32_b64 s17, s[24:25]
	s_nop 0
	v_mbcnt_lo_u32_b32 v2, s24, 0
	v_mbcnt_hi_u32_b32 v2, s25, v2
	v_cmp_gt_u32_e64 s[28:29], s16, v2
	s_and_b64 s[28:29], s[28:29], s[24:25]
	s_or_b64 s[26:27], s[26:27], s[28:29]
	s_sub_i32 s16, s16, s17
	s_max_i32 s16, s16, 0
	v_writelane_b32 v0, s26, 15
	v_writelane_b32 v1, s27, 15
	s_cmp_lt_u32 s21, 3
	s_cbranch_scc1 .Ltk_store
	v_cmp_eq_u32_e64 s[24:25], s10, v48
	v_cmp_lt_u32_e64 s[26:27], s10, v48
	s_bcnt1_i32_b64 s17, s[24:25]
	s_nop 0
	v_mbcnt_lo_u32_b32 v2, s24, 0
	v_mbcnt_hi_u32_b32 v2, s25, v2
	v_cmp_gt_u32_e64 s[28:29], s16, v2
	s_and_b64 s[28:29], s[28:29], s[24:25]
	s_or_b64 s[26:27], s[26:27], s[28:29]
	s_sub_i32 s16, s16, s17
	s_max_i32 s16, s16, 0
	v_writelane_b32 v0, s26, 16
	v_writelane_b32 v1, s27, 16
	v_cmp_eq_u32_e64 s[24:25], s10, v49
	v_cmp_lt_u32_e64 s[26:27], s10, v49
	s_bcnt1_i32_b64 s17, s[24:25]
	s_nop 0
	v_mbcnt_lo_u32_b32 v2, s24, 0
	v_mbcnt_hi_u32_b32 v2, s25, v2
	v_cmp_gt_u32_e64 s[28:29], s16, v2
	s_and_b64 s[28:29], s[28:29], s[24:25]
	s_or_b64 s[26:27], s[26:27], s[28:29]
	s_sub_i32 s16, s16, s17
	s_max_i32 s16, s16, 0
	v_writelane_b32 v0, s26, 17
	v_writelane_b32 v1, s27, 17
	v_cmp_eq_u32_e64 s[24:25], s10, v50
	v_cmp_lt_u32_e64 s[26:27], s10, v50
	s_bcnt1_i32_b64 s17, s[24:25]
	s_nop 0
	v_mbcnt_lo_u32_b32 v2, s24, 0
	v_mbcnt_hi_u32_b32 v2, s25, v2
	v_cmp_gt_u32_e64 s[28:29], s16, v2
	s_and_b64 s[28:29], s[28:29], s[24:25]
	s_or_b64 s[26:27], s[26:27], s[28:29]
	s_sub_i32 s16, s16, s17
	s_max_i32 s16, s16, 0
	v_writelane_b32 v0, s26, 18
	v_writelane_b32 v1, s27, 18
	v_cmp_eq_u32_e64 s[24:25], s10, v51
	v_cmp_lt_u32_e64 s[26:27], s10, v51
	s_bcnt1_i32_b64 s17, s[24:25]
	s_nop 0
	v_mbcnt_lo_u32_b32 v2, s24, 0
	v_mbcnt_hi_u32_b32 v2, s25, v2
	v_cmp_gt_u32_e64 s[28:29], s16, v2
	s_and_b64 s[28:29], s[28:29], s[24:25]
	s_or_b64 s[26:27], s[26:27], s[28:29]
	s_sub_i32 s16, s16, s17
	s_max_i32 s16, s16, 0
	v_writelane_b32 v0, s26, 19
	v_writelane_b32 v1, s27, 19
	v_cmp_eq_u32_e64 s[24:25], s10, v52
	v_cmp_lt_u32_e64 s[26:27], s10, v52
	s_bcnt1_i32_b64 s17, s[24:25]
	s_nop 0
	v_mbcnt_lo_u32_b32 v2, s24, 0
	v_mbcnt_hi_u32_b32 v2, s25, v2
	v_cmp_gt_u32_e64 s[28:29], s16, v2
	s_and_b64 s[28:29], s[28:29], s[24:25]
	s_or_b64 s[26:27], s[26:27], s[28:29]
	s_sub_i32 s16, s16, s17
	s_max_i32 s16, s16, 0
	v_writelane_b32 v0, s26, 20
	v_writelane_b32 v1, s27, 20
	v_cmp_eq_u32_e64 s[24:25], s10, v53
	v_cmp_lt_u32_e64 s[26:27], s10, v53
	s_bcnt1_i32_b64 s17, s[24:25]
	s_nop 0
	v_mbcnt_lo_u32_b32 v2, s24, 0
	v_mbcnt_hi_u32_b32 v2, s25, v2
	v_cmp_gt_u32_e64 s[28:29], s16, v2
	s_and_b64 s[28:29], s[28:29], s[24:25]
	s_or_b64 s[26:27], s[26:27], s[28:29]
	s_sub_i32 s16, s16, s17
	s_max_i32 s16, s16, 0
	v_writelane_b32 v0, s26, 21
	v_writelane_b32 v1, s27, 21
	v_cmp_eq_u32_e64 s[24:25], s10, v54
	v_cmp_lt_u32_e64 s[26:27], s10, v54
	s_bcnt1_i32_b64 s17, s[24:25]
	s_nop 0
	v_mbcnt_lo_u32_b32 v2, s24, 0
	v_mbcnt_hi_u32_b32 v2, s25, v2
	v_cmp_gt_u32_e64 s[28:29], s16, v2
	s_and_b64 s[28:29], s[28:29], s[24:25]
	s_or_b64 s[26:27], s[26:27], s[28:29]
	s_sub_i32 s16, s16, s17
	s_max_i32 s16, s16, 0
	v_writelane_b32 v0, s26, 22
	v_writelane_b32 v1, s27, 22
	v_cmp_eq_u32_e64 s[24:25], s10, v55
	v_cmp_lt_u32_e64 s[26:27], s10, v55
	s_bcnt1_i32_b64 s17, s[24:25]
	s_nop 0
	v_mbcnt_lo_u32_b32 v2, s24, 0
	v_mbcnt_hi_u32_b32 v2, s25, v2
	v_cmp_gt_u32_e64 s[28:29], s16, v2
	s_and_b64 s[28:29], s[28:29], s[24:25]
	s_or_b64 s[26:27], s[26:27], s[28:29]
	s_sub_i32 s16, s16, s17
	s_max_i32 s16, s16, 0
	v_writelane_b32 v0, s26, 23
	v_writelane_b32 v1, s27, 23
	s_cmp_lt_u32 s21, 4
	s_cbranch_scc1 .Ltk_store
; __device__ __forceinline__ void indexer_unit(const Args& a, LAS unsigned char* lds, LAS unsigned long long* maskl, int b, int qblk, int wave, int lane) {
;     ...
; #pragma unroll
;             for (int g = 0; g < 8; ++g) if (4 * g < nr) {
; #pragma unroll
;                 for (int k = 0; k < 4; ++k) { const int r = 4 * g + k;
;                     unsigned ur = u[r]; asm volatile("" : "+v"(ur), "+v"(myword), "+s"(need));
;                     unsigned long long m;
;                     if (exact) m = __ballot(ur >= T);
;                     else { const unsigned long long eq = __ballot(ur == T), gt = __ballot(ur > T);
;                         const bool pick = (ur == T) && (__popcll(eq & lt) < need);
;                         m = gt | __ballot(pick); need -= __popcll(eq); if (need < 0) need = 0; }
;                     if (lane == r) myword = m; } }
;         }
;         if (lane < 32) maskl[q * 32 + lane] = myword;
;     }
	v_cmp_eq_u32_e64 s[24:25], s10, v56
	v_cmp_lt_u32_e64 s[26:27], s10, v56
	s_bcnt1_i32_b64 s17, s[24:25]
	s_nop 0
	v_mbcnt_lo_u32_b32 v2, s24, 0
	v_mbcnt_hi_u32_b32 v2, s25, v2
	v_cmp_gt_u32_e64 s[28:29], s16, v2
	s_and_b64 s[28:29], s[28:29], s[24:25]
	s_or_b64 s[26:27], s[26:27], s[28:29]
	s_sub_i32 s16, s16, s17
	s_max_i32 s16, s16, 0
	v_writelane_b32 v0, s26, 24
	v_writelane_b32 v1, s27, 24
	v_cmp_eq_u32_e64 s[24:25], s10, v57
	v_cmp_lt_u32_e64 s[26:27], s10, v57
	s_bcnt1_i32_b64 s17, s[24:25]
	s_nop 0
	v_mbcnt_lo_u32_b32 v2, s24, 0
	v_mbcnt_hi_u32_b32 v2, s25, v2
	v_cmp_gt_u32_e64 s[28:29], s16, v2
	s_and_b64 s[28:29], s[28:29], s[24:25]
	s_or_b64 s[26:27], s[26:27], s[28:29]
	s_sub_i32 s16, s16, s17
	s_max_i32 s16, s16, 0
	v_writelane_b32 v0, s26, 25
	v_writelane_b32 v1, s27, 25
	v_cmp_eq_u32_e64 s[24:25], s10, v58
	v_cmp_lt_u32_e64 s[26:27], s10, v58
	s_bcnt1_i32_b64 s17, s[24:25]
	s_nop 0
	v_mbcnt_lo_u32_b32 v2, s24, 0
	v_mbcnt_hi_u32_b32 v2, s25, v2
	v_cmp_gt_u32_e64 s[28:29], s16, v2
	s_and_b64 s[28:29], s[28:29], s[24:25]
	s_or_b64 s[26:27], s[26:27], s[28:29]
	s_sub_i32 s16, s16, s17
	s_max_i32 s16, s16, 0
	v_writelane_b32 v0, s26, 26
	v_writelane_b32 v1, s27, 26
	v_cmp_eq_u32_e64 s[24:25], s10, v59
	v_cmp_lt_u32_e64 s[26:27], s10, v59
	s_bcnt1_i32_b64 s17, s[24:25]
	s_nop 0
	v_mbcnt_lo_u32_b32 v2, s24, 0
	v_mbcnt_hi_u32_b32 v2, s25, v2
	v_cmp_gt_u32_e64 s[28:29], s16, v2
	s_and_b64 s[28:29], s[28:29], s[24:25]
	s_or_b64 s[26:27], s[26:27], s[28:29]
	s_sub_i32 s16, s16, s17
	s_max_i32 s16, s16, 0
	v_writelane_b32 v0, s26, 27
	v_writelane_b32 v1, s27, 27
	v_cmp_eq_u32_e64 s[24:25], s10, v60
	v_cmp_lt_u32_e64 s[26:27], s10, v60
	s_bcnt1_i32_b64 s17, s[24:25]
	s_nop 0
	v_mbcnt_lo_u32_b32 v2, s24, 0
	v_mbcnt_hi_u32_b32 v2, s25, v2
	v_cmp_gt_u32_e64 s[28:29], s16, v2
	s_and_b64 s[28:29], s[28:29], s[24:25]
	s_or_b64 s[26:27], s[26:27], s[28:29]
	s_sub_i32 s16, s16, s17
	s_max_i32 s16, s16, 0
	v_writelane_b32 v0, s26, 28
	v_writelane_b32 v1, s27, 28
	v_cmp_eq_u32_e64 s[24:25], s10, v61
	v_cmp_lt_u32_e64 s[26:27], s10, v61
	s_bcnt1_i32_b64 s17, s[24:25]
	s_nop 0
	v_mbcnt_lo_u32_b32 v2, s24, 0
	v_mbcnt_hi_u32_b32 v2, s25, v2
	v_cmp_gt_u32_e64 s[28:29], s16, v2
	s_and_b64 s[28:29], s[28:29], s[24:25]
	s_or_b64 s[26:27], s[26:27], s[28:29]
	s_sub_i32 s16, s16, s17
	s_max_i32 s16, s16, 0
	v_writelane_b32 v0, s26, 29
	v_writelane_b32 v1, s27, 29
	v_cmp_eq_u32_e64 s[24:25], s10, v62
	v_cmp_lt_u32_e64 s[26:27], s10, v62
	s_bcnt1_i32_b64 s17, s[24:25]
	s_nop 0
	v_mbcnt_lo_u32_b32 v2, s24, 0
	v_mbcnt_hi_u32_b32 v2, s25, v2
	v_cmp_gt_u32_e64 s[28:29], s16, v2
	s_and_b64 s[28:29], s[28:29], s[24:25]
	s_or_b64 s[26:27], s[26:27], s[28:29]
	s_sub_i32 s16, s16, s17
	s_max_i32 s16, s16, 0
	v_writelane_b32 v0, s26, 30
	v_writelane_b32 v1, s27, 30
	v_cmp_eq_u32_e64 s[24:25], s10, v63
	v_cmp_lt_u32_e64 s[26:27], s10, v63
	s_bcnt1_i32_b64 s17, s[24:25]
	s_nop 0
	v_mbcnt_lo_u32_b32 v2, s24, 0
	v_mbcnt_hi_u32_b32 v2, s25, v2
	v_cmp_gt_u32_e64 s[28:29], s16, v2
	s_and_b64 s[28:29], s[28:29], s[24:25]
	s_or_b64 s[26:27], s[26:27], s[28:29]
	s_sub_i32 s16, s16, s17
	s_max_i32 s16, s16, 0
	v_writelane_b32 v0, s26, 31
	v_writelane_b32 v1, s27, 31
	s_branch .Ltk_store
.Ltk_exact:
	v_mov_b32_e32 v0, 0
	v_mov_b32_e32 v1, 0
	v_cmp_le_u32_e64 s[24:25], s10, v32
	v_cmp_le_u32_e64 s[26:27], s10, v33
	v_cmp_le_u32_e64 s[28:29], s10, v34
	v_cmp_le_u32_e64 s[30:31], s10, v35
	v_cmp_le_u32_e64 s[34:35], s10, v36
	v_cmp_le_u32_e64 s[36:37], s10, v37
	v_cmp_le_u32_e64 s[38:39], s10, v38
	v_cmp_le_u32_e64 s[40:41], s10, v39
	v_writelane_b32 v0, s24, 0
	v_writelane_b32 v1, s25, 0
	v_writelane_b32 v0, s26, 1
	v_writelane_b32 v1, s27, 1
	v_writelane_b32 v0, s28, 2
	v_writelane_b32 v1, s29, 2
	v_writelane_b32 v0, s30, 3
	v_writelane_b32 v1, s31, 3
	v_writelane_b32 v0, s34, 4
	v_writelane_b32 v1, s35, 4
	v_writelane_b32 v0, s36, 5
	v_writelane_b32 v1, s37, 5
	v_writelane_b32 v0, s38, 6
	v_writelane_b32 v1, s39, 6
	v_writelane_b32 v0, s40, 7
	v_writelane_b32 v1, s41, 7
	s_cmp_lt_u32 s21, 2
	s_cbranch_scc1 .Ltk_store
	v_cmp_le_u32_e64 s[24:25], s10, v40
	v_cmp_le_u32_e64 s[26:27], s10, v41
	v_cmp_le_u32_e64 s[28:29], s10, v42
	v_cmp_le_u32_e64 s[30:31], s10, v43
	v_cmp_le_u32_e64 s[34:35], s10, v44
	v_cmp_le_u32_e64 s[36:37], s10, v45
	v_cmp_le_u32_e64 s[38:39], s10, v46
	v_cmp_le_u32_e64 s[40:41], s10, v47
	v_writelane_b32 v0, s24, 8
	v_writelane_b32 v1, s25, 8
	v_writelane_b32 v0, s26, 9
	v_writelane_b32 v1, s27, 9
	v_writelane_b32 v0, s28, 10
	v_writelane_b32 v1, s29, 10
	v_writelane_b32 v0, s30, 11
	v_writelane_b32 v1, s31, 11
	v_writelane_b32 v0, s34, 12
	v_writelane_b32 v1, s35, 12
	v_writelane_b32 v0, s36, 13
	v_writelane_b32 v1, s37, 13
	v_writelane_b32 v0, s38, 14
	v_writelane_b32 v1, s39, 14
	v_writelane_b32 v0, s40, 15
	v_writelane_b32 v1, s41, 15
	s_cmp_lt_u32 s21, 3
	s_cbranch_scc1 .Ltk_store
	v_cmp_le_u32_e64 s[24:25], s10, v48
	v_cmp_le_u32_e64 s[26:27], s10, v49
	v_cmp_le_u32_e64 s[28:29], s10, v50
	v_cmp_le_u32_e64 s[30:31], s10, v51
	v_cmp_le_u32_e64 s[34:35], s10, v52
	v_cmp_le_u32_e64 s[36:37], s10, v53
	v_cmp_le_u32_e64 s[38:39], s10, v54
	v_cmp_le_u32_e64 s[40:41], s10, v55
	v_writelane_b32 v0, s24, 16
	v_writelane_b32 v1, s25, 16
	v_writelane_b32 v0, s26, 17
	v_writelane_b32 v1, s27, 17
	v_writelane_b32 v0, s28, 18
	v_writelane_b32 v1, s29, 18
	v_writelane_b32 v0, s30, 19
	v_writelane_b32 v1, s31, 19
	v_writelane_b32 v0, s34, 20
	v_writelane_b32 v1, s35, 20
	v_writelane_b32 v0, s36, 21
	v_writelane_b32 v1, s37, 21
	v_writelane_b32 v0, s38, 22
	v_writelane_b32 v1, s39, 22
	v_writelane_b32 v0, s40, 23
	v_writelane_b32 v1, s41, 23
	s_cmp_lt_u32 s21, 4
	s_cbranch_scc1 .Ltk_store
	v_cmp_le_u32_e64 s[24:25], s10, v56
	v_cmp_le_u32_e64 s[26:27], s10, v57
	v_cmp_le_u32_e64 s[28:29], s10, v58
	v_cmp_le_u32_e64 s[30:31], s10, v59
	v_cmp_le_u32_e64 s[34:35], s10, v60
	v_cmp_le_u32_e64 s[36:37], s10, v61
	v_cmp_le_u32_e64 s[38:39], s10, v62
	v_cmp_le_u32_e64 s[40:41], s10, v63
	v_writelane_b32 v0, s24, 24
	v_writelane_b32 v1, s25, 24
	v_writelane_b32 v0, s26, 25
	v_writelane_b32 v1, s27, 25
	v_writelane_b32 v0, s28, 26
	v_writelane_b32 v1, s29, 26
	v_writelane_b32 v0, s30, 27
	v_writelane_b32 v1, s31, 27
	v_writelane_b32 v0, s34, 28
	v_writelane_b32 v1, s35, 28
	v_writelane_b32 v0, s36, 29
	v_writelane_b32 v1, s37, 29
	v_writelane_b32 v0, s38, 30
	v_writelane_b32 v1, s39, 30
	v_writelane_b32 v0, s40, 31
	v_writelane_b32 v1, s41, 31
.Ltk_store:
	s_and_saveexec_b64 s[0:1], s[6:7]
	v_lshl_add_u32 v2, s77, 8, v66
	ds_write_b64 v2, v[0:1]
	s_mov_b64 exec, s[0:1]
	s_add_i32 s9, s9, 1
	s_cmp_lt_u32 s9, 2
	s_cbranch_scc1 .Ltk_q
	s_branch .LBB0_1081
